# K-loop heads aligned to 64B; SkHgIn lower-bound loads cached across rows (on top of HG_IN epilogue LBv hoist and X3/H3 epilogue load batching)
# speedup vs baseline: 1.0051x; 1.0035x over previous
; template <class Epi>
; __device__ __forceinline__ void gemm_phase(LAS unsigned char* lds, const Gemm g, const StaticOrder& S, const Epi& E) {
;     ...
;         const bool has_next = S.next(ui + 1, nxt);
;         const char* nA = has_next ? (const char*)g.A + (size_t)nxt.pm * tstep : cA; const char* nB = has_next ? (const char*)g.Bt + (size_t)nxt.pn * tstep : cB;
;         for (int t = 0; t < nt; t += 2) {
;             const bool last = (t == nt - 2);
;             const char* a1 = cA + (size_t)(t + 1) * kstep;
;             const char* a2 = last ? nA : cA + (size_t)(t + 2) * kstep; const char* b2 = last ? nB : cB + (size_t)(t + 2) * kstep;
;     ...
; #pragma unroll
;         for (int a = 0; a < 2; ++a)
; #pragma unroll
;             for (int b = 0; b < 2; ++b)
; #pragma unroll
;                 for (int m = 0; m < 4; ++m)
; #pragma unroll
;                     for (int n = 0; n < 2; ++n) acc[a][b][m][n] = (f32x4){0.f, 0.f, 0.f, 0.f};
.LBB0_258:
	s_ashr_i32 s9, s8, 31
	v_cmp_lt_i64_e32 vcc, s[10:11], v[140:141]
	s_lshl_b64 s[10:11], s[8:9], 20
	s_add_u32 s10, s23, s10
	s_addc_u32 s11, s24, s11
	s_and_b64 s[12:13], vcc, exec
	s_cselect_b32 s9, s11, s17
	s_cselect_b32 s63, s10, s16
	s_ashr_i32 s7, s6, 31
	s_lshl_b64 s[12:13], s[6:7], 20
	s_add_u32 s12, s25, s12
	s_addc_u32 s13, s30, s13
	s_and_b64 s[20:21], vcc, exec
	s_cselect_b32 s7, s13, s19
	s_cselect_b32 s64, s12, s18
	s_add_u32 s16, s16, 0x80080
	s_addc_u32 s17, s17, 0
	s_add_u32 s65, s18, 0x100
	v_mov_b32_e32 v0, 0
	s_addc_u32 s66, s19, 0
	s_mov_b32 s67, -2
	v_mov_b32_e32 v1, v0
	v_mov_b32_e32 v2, v0
	v_mov_b32_e32 v3, v0
	v_mov_b32_e32 v8, v0
	v_mov_b32_e32 v9, v0
	v_mov_b32_e32 v10, v0
	v_mov_b32_e32 v11, v0
	v_mov_b32_e32 v16, v0
	v_mov_b32_e32 v17, v0
	v_mov_b32_e32 v18, v0
	v_mov_b32_e32 v19, v0
	v_mov_b32_e32 v24, v0
	v_mov_b32_e32 v25, v0
	v_mov_b32_e32 v26, v0
	v_mov_b32_e32 v27, v0
	v_mov_b32_e32 v32, v0
	v_mov_b32_e32 v33, v0
	v_mov_b32_e32 v34, v0
	v_mov_b32_e32 v35, v0
	v_mov_b32_e32 v40, v0
	v_mov_b32_e32 v41, v0
	v_mov_b32_e32 v42, v0
	v_mov_b32_e32 v43, v0
	v_mov_b32_e32 v48, v0
	v_mov_b32_e32 v49, v0
	v_mov_b32_e32 v50, v0
	v_mov_b32_e32 v51, v0
	v_mov_b32_e32 v56, v0
	v_mov_b32_e32 v57, v0
	v_mov_b32_e32 v58, v0
	v_mov_b32_e32 v59, v0
	v_mov_b32_e32 v4, v0
	v_mov_b32_e32 v5, v0
	v_mov_b32_e32 v6, v0
	v_mov_b32_e32 v7, v0
	v_mov_b32_e32 v12, v0
	v_mov_b32_e32 v13, v0
	v_mov_b32_e32 v14, v0
	v_mov_b32_e32 v15, v0
	v_mov_b32_e32 v20, v0
	v_mov_b32_e32 v21, v0
	v_mov_b32_e32 v22, v0
	v_mov_b32_e32 v23, v0
	v_mov_b32_e32 v28, v0
	v_mov_b32_e32 v29, v0
	v_mov_b32_e32 v30, v0
	v_mov_b32_e32 v31, v0
	v_mov_b32_e32 v36, v0
	v_mov_b32_e32 v37, v0
	v_mov_b32_e32 v38, v0
	v_mov_b32_e32 v39, v0
	v_mov_b32_e32 v44, v0
	v_mov_b32_e32 v45, v0
	v_mov_b32_e32 v46, v0
	v_mov_b32_e32 v47, v0
	v_mov_b32_e32 v52, v0
	v_mov_b32_e32 v53, v0
	v_mov_b32_e32 v54, v0
	v_mov_b32_e32 v55, v0
	v_mov_b32_e32 v60, v0
	v_mov_b32_e32 v61, v0
	v_mov_b32_e32 v62, v0
	v_mov_b32_e32 v63, v0
	v_mov_b32_e32 v64, v0
	v_mov_b32_e32 v65, v0
	v_mov_b32_e32 v66, v0
	v_mov_b32_e32 v67, v0
	v_mov_b32_e32 v72, v0
	v_mov_b32_e32 v73, v0
	v_mov_b32_e32 v74, v0
	v_mov_b32_e32 v75, v0
	v_mov_b32_e32 v80, v0
	v_mov_b32_e32 v81, v0
	v_mov_b32_e32 v82, v0
	v_mov_b32_e32 v83, v0
	v_mov_b32_e32 v88, v0
	v_mov_b32_e32 v89, v0
	v_mov_b32_e32 v90, v0
	v_mov_b32_e32 v91, v0
	v_mov_b32_e32 v96, v0
	v_mov_b32_e32 v97, v0
	v_mov_b32_e32 v98, v0
	v_mov_b32_e32 v99, v0
	v_mov_b32_e32 v104, v0
	v_mov_b32_e32 v105, v0
	v_mov_b32_e32 v106, v0
	v_mov_b32_e32 v107, v0
	v_mov_b32_e32 v112, v0
	v_mov_b32_e32 v113, v0
	v_mov_b32_e32 v114, v0
	v_mov_b32_e32 v115, v0
	v_mov_b32_e32 v120, v0
	v_mov_b32_e32 v121, v0
	v_mov_b32_e32 v122, v0
	v_mov_b32_e32 v123, v0
	v_mov_b32_e32 v68, v0
	v_mov_b32_e32 v69, v0
	v_mov_b32_e32 v70, v0
	v_mov_b32_e32 v71, v0
	v_mov_b32_e32 v76, v0
	v_mov_b32_e32 v77, v0
	v_mov_b32_e32 v78, v0
	v_mov_b32_e32 v79, v0
	v_mov_b32_e32 v84, v0
	v_mov_b32_e32 v85, v0
	v_mov_b32_e32 v86, v0
	v_mov_b32_e32 v87, v0
	v_mov_b32_e32 v92, v0
	v_mov_b32_e32 v93, v0
	v_mov_b32_e32 v94, v0
	v_mov_b32_e32 v95, v0
	v_mov_b32_e32 v100, v0
	v_mov_b32_e32 v101, v0
	v_mov_b32_e32 v102, v0
	v_mov_b32_e32 v103, v0
	v_mov_b32_e32 v108, v0
	v_mov_b32_e32 v109, v0
	v_mov_b32_e32 v110, v0
	v_mov_b32_e32 v111, v0
	v_mov_b32_e32 v116, v0
	v_mov_b32_e32 v117, v0
	v_mov_b32_e32 v118, v0
	v_mov_b32_e32 v119, v0
	v_mov_b32_e32 v124, v0
	v_mov_b32_e32 v125, v0
	v_mov_b32_e32 v126, v0
	v_mov_b32_e32 v127, v0
	.p2align	6

; template <class Epi>
; __device__ __forceinline__ void gemm_phase(LAS unsigned char* lds, const Gemm g, const StaticOrder& S, const Epi& E) {
;     ...
;         for (int t = 0; t < nt; t += 2) {
;             const bool last = (t == nt - 2);
;             const char* a1 = cA + (size_t)(t + 1) * kstep;
;             const char* a2 = last ? nA : cA + (size_t)(t + 2) * kstep; const char* b2 = last ? nB : cB + (size_t)(t + 2) * kstep;
;             const char* a3 = a2 + kstep; const char* b3 = b2 + kstep;
;     ...
; #pragma unroll
;         for (int a = 0; a < 2; ++a)
; #pragma unroll
;             for (int b = 0; b < 2; ++b)
; #pragma unroll
;                 for (int m = 0; m < 4; ++m)
; #pragma unroll
;                     for (int n = 0; n < 2; ++n) acc[a][b][m][n] = (f32x4){0.f, 0.f, 0.f, 0.f};
.LBB0_363:
	s_add_u32 s14, s14, 0x158080
	s_addc_u32 s15, s15, 0
	s_add_u32 s63, s16, 0x100
	v_mov_b32_e32 v0, 0
	s_addc_u32 s64, s17, 0
	s_mov_b32 s65, -2
	s_waitcnt lgkmcnt(0)
	v_mov_b32_e32 v1, v0
	v_mov_b32_e32 v2, v0
	v_mov_b32_e32 v3, v0
	v_mov_b32_e32 v4, v0
	v_mov_b32_e32 v5, v0
	v_mov_b32_e32 v6, v0
	v_mov_b32_e32 v7, v0
	v_mov_b32_e32 v16, v0
	v_mov_b32_e32 v17, v0
	v_mov_b32_e32 v18, v0
	v_mov_b32_e32 v19, v0
	v_mov_b32_e32 v20, v0
	v_mov_b32_e32 v21, v0
	v_mov_b32_e32 v22, v0
	v_mov_b32_e32 v23, v0
	v_mov_b32_e32 v32, v0
	v_mov_b32_e32 v33, v0
	v_mov_b32_e32 v34, v0
	v_mov_b32_e32 v35, v0
	v_mov_b32_e32 v36, v0
	v_mov_b32_e32 v37, v0
	v_mov_b32_e32 v38, v0
	v_mov_b32_e32 v39, v0
	v_mov_b32_e32 v48, v0
	v_mov_b32_e32 v49, v0
	v_mov_b32_e32 v50, v0
	v_mov_b32_e32 v51, v0
	v_mov_b32_e32 v52, v0
	v_mov_b32_e32 v53, v0
	v_mov_b32_e32 v54, v0
	v_mov_b32_e32 v55, v0
	v_mov_b32_e32 v8, v0
	v_mov_b32_e32 v9, v0
	v_mov_b32_e32 v10, v0
	v_mov_b32_e32 v11, v0
	v_mov_b32_e32 v12, v0
	v_mov_b32_e32 v13, v0
	v_mov_b32_e32 v14, v0
	v_mov_b32_e32 v15, v0
	v_mov_b32_e32 v24, v0
	v_mov_b32_e32 v25, v0
	v_mov_b32_e32 v26, v0
	v_mov_b32_e32 v27, v0
	v_mov_b32_e32 v28, v0
	v_mov_b32_e32 v29, v0
	v_mov_b32_e32 v30, v0
	v_mov_b32_e32 v31, v0
	v_mov_b32_e32 v40, v0
	v_mov_b32_e32 v41, v0
	v_mov_b32_e32 v42, v0
	v_mov_b32_e32 v43, v0
	v_mov_b32_e32 v44, v0
	v_mov_b32_e32 v45, v0
	v_mov_b32_e32 v46, v0
	v_mov_b32_e32 v47, v0
	v_mov_b32_e32 v56, v0
	v_mov_b32_e32 v57, v0
	v_mov_b32_e32 v58, v0
	v_mov_b32_e32 v59, v0
	v_mov_b32_e32 v60, v0
	v_mov_b32_e32 v61, v0
	v_mov_b32_e32 v62, v0
	v_mov_b32_e32 v63, v0
	v_mov_b32_e32 v64, v0
	v_mov_b32_e32 v65, v0
	v_mov_b32_e32 v66, v0
	v_mov_b32_e32 v67, v0
	v_mov_b32_e32 v68, v0
	v_mov_b32_e32 v69, v0
	v_mov_b32_e32 v70, v0
	v_mov_b32_e32 v71, v0
	v_mov_b32_e32 v80, v0
	v_mov_b32_e32 v81, v0
	v_mov_b32_e32 v82, v0
	v_mov_b32_e32 v83, v0
	v_mov_b32_e32 v84, v0
	v_mov_b32_e32 v85, v0
	v_mov_b32_e32 v86, v0
	v_mov_b32_e32 v87, v0
	v_mov_b32_e32 v96, v0
	v_mov_b32_e32 v97, v0
	v_mov_b32_e32 v98, v0
	v_mov_b32_e32 v99, v0
	v_mov_b32_e32 v100, v0
	v_mov_b32_e32 v101, v0
	v_mov_b32_e32 v102, v0
	v_mov_b32_e32 v103, v0
	v_mov_b32_e32 v112, v0
	v_mov_b32_e32 v113, v0
	v_mov_b32_e32 v114, v0
	v_mov_b32_e32 v115, v0
	v_mov_b32_e32 v116, v0
	v_mov_b32_e32 v117, v0
	v_mov_b32_e32 v118, v0
	v_mov_b32_e32 v119, v0
	v_mov_b32_e32 v72, v0
	v_mov_b32_e32 v73, v0
	v_mov_b32_e32 v74, v0
	v_mov_b32_e32 v75, v0
	v_mov_b32_e32 v76, v0
	v_mov_b32_e32 v77, v0
	v_mov_b32_e32 v78, v0
	v_mov_b32_e32 v79, v0
	v_mov_b32_e32 v88, v0
	v_mov_b32_e32 v89, v0
	v_mov_b32_e32 v90, v0
	v_mov_b32_e32 v91, v0
	v_mov_b32_e32 v92, v0
	v_mov_b32_e32 v93, v0
	v_mov_b32_e32 v94, v0
	v_mov_b32_e32 v95, v0
	v_mov_b32_e32 v104, v0
	v_mov_b32_e32 v105, v0
	v_mov_b32_e32 v106, v0
	v_mov_b32_e32 v107, v0
	v_mov_b32_e32 v108, v0
	v_mov_b32_e32 v109, v0
	v_mov_b32_e32 v110, v0
	v_mov_b32_e32 v111, v0
	v_mov_b32_e32 v120, v0
	v_mov_b32_e32 v121, v0
	v_mov_b32_e32 v122, v0
	v_mov_b32_e32 v123, v0
	v_mov_b32_e32 v124, v0
	v_mov_b32_e32 v125, v0
	v_mov_b32_e32 v126, v0
	v_mov_b32_e32 v127, v0
	.p2align	6

.LBB0_462:
	v_lshlrev_b32_e32 v100, 2, v143
	global_load_dword v100, v100, s[24:25]
	v_mul_f32_e32 v101, 0xbfb8aa3b, v96
	v_exp_f32_e32 v101, v101
	v_lshlrev_b32_e32 v104, 1, v152
	v_add_f32_e32 v101, 1.0, v101
	v_rcp_f32_e32 v101, v101
	s_waitcnt vmcnt(0)
	v_mov_b32_e32 v240, v100
	v_sub_f32_e32 v105, 1.0, v100
	v_fmac_f32_e32 v100, v101, v105
	v_cmp_gt_f32_e32 vcc, s57, v100
	v_sub_f32_e32 v101, 1.0, v100
	v_cvt_pk_bf16_f32 v101, v101, s0
	v_cndmask_b32_e64 v105, 0, 32, vcc
	v_ldexp_f32 v100, v100, v105
	v_log_f32_e32 v100, v100
	global_store_short v104, v101, s[16:17]
	v_cndmask_b32_e32 v105, 0, v151, vcc
	v_mul_f32_e32 v101, 0x3f317217, v100
	v_fma_f32 v101, v100, s58, -v101
	v_fmac_f32_e32 v101, 0x3377d1cf, v100
	v_fmac_f32_e32 v101, 0x3f317217, v100
	v_cmp_lt_f32_e64 vcc, |v100|, s59
	s_nop 1
	v_cndmask_b32_e32 v100, v100, v101, vcc
	v_sub_f32_e32 v100, v100, v105
	v_lshlrev_b32_e32 v101, 2, v152
	global_store_dword v101, v100, s[22:23]

.LBB0_476:
	v_lshlrev_b32_e32 v72, 2, v68
	global_load_dword v72, v72, s[24:25]
	v_mul_f32_e32 v73, 0xbfb8aa3b, v64
	v_exp_f32_e32 v73, v73
	v_lshlrev_b32_e32 v76, 1, v69
	v_add_f32_e32 v73, 1.0, v73
	v_rcp_f32_e32 v73, v73
	s_waitcnt vmcnt(0)
	v_mov_b32_e32 v241, v72
	v_sub_f32_e32 v77, 1.0, v72
	v_fmac_f32_e32 v72, v73, v77
	v_cmp_gt_f32_e32 vcc, s57, v72
	v_sub_f32_e32 v73, 1.0, v72
	v_cvt_pk_bf16_f32 v73, v73, s0
	v_cndmask_b32_e64 v77, 0, 32, vcc
	v_ldexp_f32 v72, v72, v77
	v_log_f32_e32 v72, v72
	global_store_short v76, v73, s[16:17]
	v_cndmask_b32_e32 v77, 0, v151, vcc
	v_mul_f32_e32 v73, 0x3f317217, v72
	v_fma_f32 v73, v72, s58, -v73
	v_fmac_f32_e32 v73, 0x3377d1cf, v72
	v_fmac_f32_e32 v73, 0x3f317217, v72
	v_cmp_lt_f32_e64 vcc, |v72|, s59
	s_nop 1
	v_cndmask_b32_e32 v72, v72, v73, vcc
	v_sub_f32_e32 v72, v72, v77
	v_lshlrev_b32_e32 v73, 2, v69
	global_store_dword v73, v72, s[22:23]

.LBB0_490:
	v_lshlrev_b32_e32 v40, 2, v36
	global_load_dword v40, v40, s[24:25]
	v_mul_f32_e32 v41, 0xbfb8aa3b, v32
	v_exp_f32_e32 v41, v41
	v_lshlrev_b32_e32 v44, 1, v37
	v_add_f32_e32 v41, 1.0, v41
	v_rcp_f32_e32 v41, v41
	s_waitcnt vmcnt(0)
	v_mov_b32_e32 v242, v40
	v_sub_f32_e32 v45, 1.0, v40
	v_fmac_f32_e32 v40, v41, v45
	v_cmp_gt_f32_e32 vcc, s57, v40
	v_sub_f32_e32 v41, 1.0, v40
	v_cvt_pk_bf16_f32 v41, v41, s0
	v_cndmask_b32_e64 v45, 0, 32, vcc
	v_ldexp_f32 v40, v40, v45
	v_log_f32_e32 v40, v40
	global_store_short v44, v41, s[16:17]
	v_cndmask_b32_e32 v45, 0, v151, vcc
	v_mul_f32_e32 v41, 0x3f317217, v40
	v_fma_f32 v41, v40, s58, -v41
	v_fmac_f32_e32 v41, 0x3377d1cf, v40
	v_fmac_f32_e32 v41, 0x3f317217, v40
	v_cmp_lt_f32_e64 vcc, |v40|, s59
	s_nop 1
	v_cndmask_b32_e32 v40, v40, v41, vcc
	v_sub_f32_e32 v40, v40, v45
	v_lshlrev_b32_e32 v41, 2, v37
	global_store_dword v41, v40, s[22:23]

.LBB0_504:
	v_lshlrev_b32_e32 v4, 2, v16
	global_load_dword v4, v4, s[24:25]
	v_mul_f32_e32 v5, 0xbfb8aa3b, v1
	v_exp_f32_e32 v5, v5
	v_lshlrev_b32_e32 v8, 1, v0
	v_add_f32_e32 v5, 1.0, v5
	v_rcp_f32_e32 v5, v5
	s_waitcnt vmcnt(0)
	v_mov_b32_e32 v243, v4
	v_sub_f32_e32 v9, 1.0, v4
	v_fmac_f32_e32 v4, v5, v9
	v_cmp_gt_f32_e32 vcc, s57, v4
	v_sub_f32_e32 v5, 1.0, v4
	v_cvt_pk_bf16_f32 v5, v5, s0
	v_cndmask_b32_e64 v9, 0, 32, vcc
	v_ldexp_f32 v4, v4, v9
	v_log_f32_e32 v4, v4
	global_store_short v8, v5, s[16:17]
	v_cndmask_b32_e32 v9, 0, v151, vcc
	v_mul_f32_e32 v5, 0x3f317217, v4
	v_fma_f32 v5, v4, s58, -v5
	v_fmac_f32_e32 v5, 0x3377d1cf, v4
	v_fmac_f32_e32 v5, 0x3f317217, v4
	v_cmp_lt_f32_e64 vcc, |v4|, s59
	s_nop 1
	v_cndmask_b32_e32 v4, v4, v5, vcc
	v_sub_f32_e32 v4, v4, v9
	v_lshlrev_b32_e32 v5, 2, v0
	global_store_dword v5, v4, s[22:23]

.LBB0_518:
	v_lshlrev_b32_e32 v8, 2, v143
	v_mov_b32_e32 v8, v240
	v_mul_f32_e32 v9, 0xbfb8aa3b, v5
	v_exp_f32_e32 v9, v9
	v_lshlrev_b32_e32 v17, 1, v4
	v_add_f32_e32 v9, 1.0, v9
	v_rcp_f32_e32 v9, v9

	v_sub_f32_e32 v20, 1.0, v8
	v_fmac_f32_e32 v8, v9, v20
	v_cmp_gt_f32_e32 vcc, s57, v8
	v_sub_f32_e32 v9, 1.0, v8
	v_cvt_pk_bf16_f32 v9, v9, s0
	v_cndmask_b32_e64 v20, 0, 32, vcc
	v_ldexp_f32 v8, v8, v20
	v_log_f32_e32 v8, v8
	global_store_short v17, v9, s[16:17]
	v_cndmask_b32_e32 v20, 0, v151, vcc
	v_mul_f32_e32 v9, 0x3f317217, v8
	v_fma_f32 v9, v8, s58, -v9
	v_fmac_f32_e32 v9, 0x3377d1cf, v8
	v_fmac_f32_e32 v9, 0x3f317217, v8
	v_cmp_lt_f32_e64 vcc, |v8|, s59
	s_nop 1
	v_cndmask_b32_e32 v8, v8, v9, vcc
	v_sub_f32_e32 v8, v8, v20
	v_lshlrev_b32_e32 v9, 2, v4
	global_store_dword v9, v8, s[22:23]

.LBB0_532:
	v_lshlrev_b32_e32 v17, 2, v68
	v_mov_b32_e32 v17, v241
	v_mul_f32_e32 v20, 0xbfb8aa3b, v9
	v_exp_f32_e32 v20, v20
	v_lshlrev_b32_e32 v21, 1, v8
	v_add_f32_e32 v20, 1.0, v20
	v_rcp_f32_e32 v20, v20

	v_sub_f32_e32 v24, 1.0, v17
	v_fmac_f32_e32 v17, v20, v24
	v_cmp_gt_f32_e32 vcc, s57, v17
	v_sub_f32_e32 v20, 1.0, v17
	v_cvt_pk_bf16_f32 v20, v20, s0
	v_cndmask_b32_e64 v24, 0, 32, vcc
	v_ldexp_f32 v17, v17, v24
	v_log_f32_e32 v17, v17
	global_store_short v21, v20, s[16:17]
	v_cndmask_b32_e32 v24, 0, v151, vcc
	v_mul_f32_e32 v20, 0x3f317217, v17
	v_fma_f32 v20, v17, s58, -v20
	v_fmac_f32_e32 v20, 0x3377d1cf, v17
	v_fmac_f32_e32 v20, 0x3f317217, v17
	v_cmp_lt_f32_e64 vcc, |v17|, s59
	s_nop 1
	v_cndmask_b32_e32 v17, v17, v20, vcc
	v_sub_f32_e32 v17, v17, v24
	v_lshlrev_b32_e32 v20, 2, v8
	global_store_dword v20, v17, s[22:23]

.LBB0_546:
	v_lshlrev_b32_e32 v21, 2, v36
	v_mov_b32_e32 v21, v242
	v_mul_f32_e32 v24, 0xbfb8aa3b, v20
	v_exp_f32_e32 v24, v24
	v_lshlrev_b32_e32 v25, 1, v17
	v_add_f32_e32 v24, 1.0, v24
	v_rcp_f32_e32 v24, v24

	v_sub_f32_e32 v28, 1.0, v21
	v_fmac_f32_e32 v21, v24, v28
	v_cmp_gt_f32_e32 vcc, s57, v21
	v_sub_f32_e32 v24, 1.0, v21
	v_cvt_pk_bf16_f32 v24, v24, s0
	v_cndmask_b32_e64 v28, 0, 32, vcc
	v_ldexp_f32 v21, v21, v28
	v_log_f32_e32 v21, v21
	global_store_short v25, v24, s[16:17]
	v_cndmask_b32_e32 v28, 0, v151, vcc
	v_mul_f32_e32 v24, 0x3f317217, v21
	v_fma_f32 v24, v21, s58, -v24
	v_fmac_f32_e32 v24, 0x3377d1cf, v21
	v_fmac_f32_e32 v24, 0x3f317217, v21
	v_cmp_lt_f32_e64 vcc, |v21|, s59
	s_nop 1
	v_cndmask_b32_e32 v21, v21, v24, vcc
	v_sub_f32_e32 v21, v21, v28
	v_lshlrev_b32_e32 v24, 2, v17
	global_store_dword v24, v21, s[22:23]

.LBB0_560:
	v_lshlrev_b32_e32 v10, 2, v16
	v_mov_b32_e32 v10, v243
	v_mul_f32_e32 v11, 0xbfb8aa3b, v7
	v_exp_f32_e32 v11, v11
	v_lshlrev_b32_e32 v12, 1, v6
	v_add_f32_e32 v11, 1.0, v11
	v_rcp_f32_e32 v11, v11

	v_sub_f32_e32 v13, 1.0, v10
	v_fmac_f32_e32 v10, v11, v13
	v_cmp_gt_f32_e32 vcc, s57, v10
	v_sub_f32_e32 v11, 1.0, v10
	v_cvt_pk_bf16_f32 v11, v11, s0
	v_cndmask_b32_e64 v13, 0, 32, vcc
	v_ldexp_f32 v10, v10, v13
	v_log_f32_e32 v10, v10
	global_store_short v12, v11, s[16:17]
	v_cndmask_b32_e32 v13, 0, v151, vcc
	v_mul_f32_e32 v11, 0x3f317217, v10
	v_fma_f32 v11, v10, s58, -v11
	v_fmac_f32_e32 v11, 0x3377d1cf, v10
	v_fmac_f32_e32 v11, 0x3f317217, v10
	v_cmp_lt_f32_e64 vcc, |v10|, s59
	s_nop 1
	v_cndmask_b32_e32 v10, v10, v11, vcc
	v_sub_f32_e32 v10, v10, v13
	v_lshlrev_b32_e32 v11, 2, v6
	global_store_dword v11, v10, s[22:23]

.LBB0_574:
	v_lshlrev_b32_e32 v10, 2, v143
	v_mov_b32_e32 v10, v240
	v_mul_f32_e32 v11, 0xbfb8aa3b, v0
	v_exp_f32_e32 v11, v11
	v_lshlrev_b32_e32 v12, 1, v7
	v_add_f32_e32 v11, 1.0, v11
	v_rcp_f32_e32 v11, v11

	v_sub_f32_e32 v13, 1.0, v10
	v_fmac_f32_e32 v10, v11, v13
	v_cmp_gt_f32_e32 vcc, s57, v10
	v_sub_f32_e32 v11, 1.0, v10
	v_cvt_pk_bf16_f32 v11, v11, s0
	v_cndmask_b32_e64 v13, 0, 32, vcc
	v_ldexp_f32 v10, v10, v13
	v_log_f32_e32 v10, v10
	global_store_short v12, v11, s[16:17]
	v_cndmask_b32_e32 v13, 0, v151, vcc
	v_mul_f32_e32 v11, 0x3f317217, v10
	v_fma_f32 v11, v10, s58, -v11
	v_fmac_f32_e32 v11, 0x3377d1cf, v10
	v_fmac_f32_e32 v11, 0x3f317217, v10
	v_cmp_lt_f32_e64 vcc, |v10|, s59
	s_nop 1
	v_cndmask_b32_e32 v10, v10, v11, vcc
	v_sub_f32_e32 v10, v10, v13
	v_lshlrev_b32_e32 v11, 2, v7
	global_store_dword v11, v10, s[22:23]

.LBB0_588:
	v_lshlrev_b32_e32 v7, 2, v68
	v_mov_b32_e32 v7, v241
	v_mul_f32_e32 v10, 0xbfb8aa3b, v4
	v_exp_f32_e32 v10, v10
	v_lshlrev_b32_e32 v11, 1, v0
	v_add_f32_e32 v10, 1.0, v10
	v_rcp_f32_e32 v10, v10

	v_sub_f32_e32 v12, 1.0, v7
	v_fmac_f32_e32 v7, v10, v12
	v_cmp_gt_f32_e32 vcc, s57, v7
	v_sub_f32_e32 v10, 1.0, v7
	v_cvt_pk_bf16_f32 v10, v10, s0
	v_cndmask_b32_e64 v12, 0, 32, vcc
	v_ldexp_f32 v7, v7, v12
	v_log_f32_e32 v7, v7
	global_store_short v11, v10, s[16:17]
	v_cndmask_b32_e32 v12, 0, v151, vcc
	v_mul_f32_e32 v10, 0x3f317217, v7
	v_fma_f32 v10, v7, s58, -v10
	v_fmac_f32_e32 v10, 0x3377d1cf, v7
	v_fmac_f32_e32 v10, 0x3f317217, v7
	v_cmp_lt_f32_e64 vcc, |v7|, s59
	s_nop 1
	v_cndmask_b32_e32 v7, v7, v10, vcc
	v_sub_f32_e32 v7, v7, v12
	v_lshlrev_b32_e32 v10, 2, v0
	global_store_dword v10, v7, s[22:23]

.LBB0_602:
	v_lshlrev_b32_e32 v7, 2, v36
	v_mov_b32_e32 v7, v242
	v_mul_f32_e32 v8, 0xbfb8aa3b, v4
	v_exp_f32_e32 v8, v8
	v_lshlrev_b32_e32 v10, 1, v0
	v_add_f32_e32 v8, 1.0, v8
	v_rcp_f32_e32 v8, v8

	v_sub_f32_e32 v11, 1.0, v7
	v_fmac_f32_e32 v7, v8, v11
	v_cmp_gt_f32_e32 vcc, s57, v7
	v_sub_f32_e32 v8, 1.0, v7
	v_cvt_pk_bf16_f32 v8, v8, s0
	v_cndmask_b32_e64 v11, 0, 32, vcc
	v_ldexp_f32 v7, v7, v11
	v_log_f32_e32 v7, v7
	global_store_short v10, v8, s[16:17]
	v_cndmask_b32_e32 v11, 0, v151, vcc
	v_mul_f32_e32 v8, 0x3f317217, v7
	v_fma_f32 v8, v7, s58, -v8
	v_fmac_f32_e32 v8, 0x3377d1cf, v7
	v_fmac_f32_e32 v8, 0x3f317217, v7
	v_cmp_lt_f32_e64 vcc, |v7|, s59
	s_nop 1
	v_cndmask_b32_e32 v7, v7, v8, vcc
	v_sub_f32_e32 v7, v7, v11
	v_lshlrev_b32_e32 v8, 2, v0
	global_store_dword v8, v7, s[22:23]

.LBB0_616:
	v_lshlrev_b32_e32 v4, 2, v16
	v_mov_b32_e32 v4, v243
	v_mul_f32_e32 v6, 0xbfb8aa3b, v2
	v_exp_f32_e32 v6, v6
	v_lshlrev_b32_e32 v7, 1, v0
	v_add_f32_e32 v6, 1.0, v6
	v_rcp_f32_e32 v6, v6

	v_sub_f32_e32 v8, 1.0, v4
	v_fmac_f32_e32 v4, v6, v8
	v_cmp_gt_f32_e32 vcc, s57, v4
	v_sub_f32_e32 v6, 1.0, v4
	v_cvt_pk_bf16_f32 v6, v6, s0
	v_cndmask_b32_e64 v8, 0, 32, vcc
	v_ldexp_f32 v4, v4, v8
	v_log_f32_e32 v4, v4
	global_store_short v7, v6, s[16:17]
	v_cndmask_b32_e32 v8, 0, v151, vcc
	v_mul_f32_e32 v6, 0x3f317217, v4
	v_fma_f32 v6, v4, s58, -v6
	v_fmac_f32_e32 v6, 0x3377d1cf, v4
	v_fmac_f32_e32 v6, 0x3f317217, v4
	v_cmp_lt_f32_e64 vcc, |v4|, s59
	s_nop 1
	v_cndmask_b32_e32 v4, v4, v6, vcc
	v_sub_f32_e32 v4, v4, v8
	v_lshlrev_b32_e32 v6, 2, v0
	global_store_dword v6, v4, s[22:23]

.LBB0_630:
	v_lshlrev_b32_e32 v4, 2, v143
	v_mov_b32_e32 v4, v240
	v_mul_f32_e32 v6, 0xbfb8aa3b, v1
	v_exp_f32_e32 v6, v6
	v_lshlrev_b32_e32 v7, 1, v2
	v_add_f32_e32 v6, 1.0, v6
	v_rcp_f32_e32 v6, v6

	v_sub_f32_e32 v8, 1.0, v4
	v_fmac_f32_e32 v4, v6, v8
	v_cmp_gt_f32_e32 vcc, s57, v4
	v_sub_f32_e32 v6, 1.0, v4
	v_cvt_pk_bf16_f32 v6, v6, s0
	v_cndmask_b32_e64 v8, 0, 32, vcc
	v_ldexp_f32 v4, v4, v8
	v_log_f32_e32 v4, v4
	global_store_short v7, v6, s[16:17]
	v_cndmask_b32_e32 v8, 0, v151, vcc
	v_mul_f32_e32 v6, 0x3f317217, v4
	v_fma_f32 v6, v4, s58, -v6
	v_fmac_f32_e32 v6, 0x3377d1cf, v4
	v_fmac_f32_e32 v6, 0x3f317217, v4
	v_cmp_lt_f32_e64 vcc, |v4|, s59
	s_nop 1
	v_cndmask_b32_e32 v4, v4, v6, vcc
	v_sub_f32_e32 v4, v4, v8
	v_lshlrev_b32_e32 v6, 2, v2
	global_store_dword v6, v4, s[22:23]

.LBB0_644:
	v_lshlrev_b32_e32 v4, 2, v68
	v_mov_b32_e32 v4, v241
	v_mul_f32_e32 v5, 0xbfb8aa3b, v2
	v_exp_f32_e32 v5, v5
	v_lshlrev_b32_e32 v6, 1, v1
	v_add_f32_e32 v5, 1.0, v5
	v_rcp_f32_e32 v5, v5

	v_sub_f32_e32 v7, 1.0, v4
	v_fmac_f32_e32 v4, v5, v7
	v_cmp_gt_f32_e32 vcc, s57, v4
	v_sub_f32_e32 v5, 1.0, v4
	v_cvt_pk_bf16_f32 v5, v5, s0
	v_cndmask_b32_e64 v7, 0, 32, vcc
	v_ldexp_f32 v4, v4, v7
	v_log_f32_e32 v4, v4
	global_store_short v6, v5, s[16:17]
	v_cndmask_b32_e32 v7, 0, v151, vcc
	v_mul_f32_e32 v5, 0x3f317217, v4
	v_fma_f32 v5, v4, s58, -v5
	v_fmac_f32_e32 v5, 0x3377d1cf, v4
	v_fmac_f32_e32 v5, 0x3f317217, v4
	v_cmp_lt_f32_e64 vcc, |v4|, s59
	s_nop 1
	v_cndmask_b32_e32 v4, v4, v5, vcc
	v_sub_f32_e32 v4, v4, v7
	v_lshlrev_b32_e32 v5, 2, v1
	global_store_dword v5, v4, s[22:23]

.LBB0_658:
	v_lshlrev_b32_e32 v4, 2, v36
	v_mov_b32_e32 v4, v242
	v_mul_f32_e32 v5, 0xbfb8aa3b, v2
	v_exp_f32_e32 v5, v5
	v_lshlrev_b32_e32 v6, 1, v1
	v_add_f32_e32 v5, 1.0, v5
	v_rcp_f32_e32 v5, v5

	v_sub_f32_e32 v7, 1.0, v4
	v_fmac_f32_e32 v4, v5, v7
	v_cmp_gt_f32_e32 vcc, s57, v4
	v_sub_f32_e32 v5, 1.0, v4
	v_cvt_pk_bf16_f32 v5, v5, s0
	v_cndmask_b32_e64 v7, 0, 32, vcc
	v_ldexp_f32 v4, v4, v7
	v_log_f32_e32 v4, v4
	global_store_short v6, v5, s[16:17]
	v_cndmask_b32_e32 v7, 0, v151, vcc
	v_mul_f32_e32 v5, 0x3f317217, v4
	v_fma_f32 v5, v4, s58, -v5
	v_fmac_f32_e32 v5, 0x3377d1cf, v4
	v_fmac_f32_e32 v5, 0x3f317217, v4
	v_cmp_lt_f32_e64 vcc, |v4|, s59
	s_nop 1
	v_cndmask_b32_e32 v4, v4, v5, vcc
	v_sub_f32_e32 v4, v4, v7
	v_lshlrev_b32_e32 v5, 2, v1
	global_store_dword v5, v4, s[22:23]

.LBB0_672:
	v_lshlrev_b32_e32 v2, 2, v16
	v_mov_b32_e32 v2, v243
	v_mul_f32_e32 v3, 0xbfb8aa3b, v0
	v_exp_f32_e32 v3, v3
	v_lshlrev_b32_e32 v4, 1, v1
	v_add_f32_e32 v3, 1.0, v3
	v_rcp_f32_e32 v3, v3

	v_sub_f32_e32 v5, 1.0, v2
	v_fmac_f32_e32 v2, v3, v5
	v_cmp_gt_f32_e32 vcc, s57, v2
	v_sub_f32_e32 v3, 1.0, v2
	v_cvt_pk_bf16_f32 v3, v3, s0
	v_cndmask_b32_e64 v5, 0, 32, vcc
	v_ldexp_f32 v2, v2, v5
	v_log_f32_e32 v2, v2
	global_store_short v4, v3, s[16:17]
	v_cndmask_b32_e32 v5, 0, v151, vcc
	v_mul_f32_e32 v3, 0x3f317217, v2
	v_fma_f32 v3, v2, s58, -v3
	v_fmac_f32_e32 v3, 0x3377d1cf, v2
	v_fmac_f32_e32 v3, 0x3f317217, v2
	v_cmp_lt_f32_e64 vcc, |v2|, s59
	s_nop 1
	v_cndmask_b32_e32 v2, v2, v3, vcc
	v_sub_f32_e32 v2, v2, v5
	v_lshlrev_b32_e32 v3, 2, v1
	global_store_dword v3, v2, s[22:23]

; template <class Epi>
; __device__ __forceinline__ void gemm_phase(LAS unsigned char* lds, const Gemm g, const StaticOrder& S, const Epi& E) {
;     ...
;         const bool has_next = S.next(ui + 1, nxt);
;         const char* nA = has_next ? (const char*)g.A + (size_t)nxt.pm * tstep : cA; const char* nB = has_next ? (const char*)g.Bt + (size_t)nxt.pn * tstep : cB;
;         for (int t = 0; t < nt; t += 2) {
;             const bool last = (t == nt - 2);
;             const char* a1 = cA + (size_t)(t + 1) * kstep;
;             const char* a2 = last ? nA : cA + (size_t)(t + 2) * kstep; const char* b2 = last ? nB : cB + (size_t)(t + 2) * kstep;
;     ...
; #pragma unroll
;         for (int a = 0; a < 2; ++a)
; #pragma unroll
;             for (int b = 0; b < 2; ++b)
; #pragma unroll
;                 for (int m = 0; m < 4; ++m)
; #pragma unroll
;                     for (int n = 0; n < 2; ++n) acc[a][b][m][n] = (f32x4){0.f, 0.f, 0.f, 0.f};
.LBB0_690:
	s_ashr_i32 s63, s62, 31
	s_lshl_b64 s[10:11], s[62:63], 20
	s_add_u32 s64, s70, s10
	v_cmp_lt_i64_e64 s[2:3], s[2:3], v[144:145]
	s_addc_u32 s65, s71, s11
	s_and_b64 s[10:11], s[2:3], exec
	s_cselect_b32 s1, s65, s7
	s_cselect_b32 s5, s64, s6
	s_ashr_i32 s61, s60, 31
	s_lshl_b64 s[10:11], s[60:61], 20
	s_add_u32 s66, s72, s10
	s_addc_u32 s67, s73, s11
	s_and_b64 s[10:11], s[2:3], exec
	s_cselect_b32 s12, s67, s9
	s_cselect_b32 s13, s66, s8
	s_add_u32 s6, s6, 0x80080
	s_addc_u32 s7, s7, 0
	s_add_u32 s33, s8, 0x100
	v_mov_b32_e32 v0, 0
	s_addc_u32 s61, s9, 0
	s_mov_b32 s63, -2
	v_mov_b32_e32 v1, v0
	v_mov_b32_e32 v2, v0
	v_mov_b32_e32 v3, v0
	v_mov_b32_e32 v4, v0
	v_mov_b32_e32 v5, v0
	v_mov_b32_e32 v6, v0
	v_mov_b32_e32 v7, v0
	v_mov_b32_e32 v16, v0
	v_mov_b32_e32 v17, v0
	v_mov_b32_e32 v18, v0
	v_mov_b32_e32 v19, v0
	v_mov_b32_e32 v20, v0
	v_mov_b32_e32 v21, v0
	v_mov_b32_e32 v22, v0
	v_mov_b32_e32 v23, v0
	v_mov_b32_e32 v32, v0
	v_mov_b32_e32 v33, v0
	v_mov_b32_e32 v34, v0
	v_mov_b32_e32 v35, v0
	v_mov_b32_e32 v36, v0
	v_mov_b32_e32 v37, v0
	v_mov_b32_e32 v38, v0
	v_mov_b32_e32 v39, v0
	v_mov_b32_e32 v48, v0
	v_mov_b32_e32 v49, v0
	v_mov_b32_e32 v50, v0
	v_mov_b32_e32 v51, v0
	v_mov_b32_e32 v52, v0
	v_mov_b32_e32 v53, v0
	v_mov_b32_e32 v54, v0
	v_mov_b32_e32 v55, v0
	v_mov_b32_e32 v8, v0
	v_mov_b32_e32 v9, v0
	v_mov_b32_e32 v10, v0
	v_mov_b32_e32 v11, v0
	v_mov_b32_e32 v12, v0
	v_mov_b32_e32 v13, v0
	v_mov_b32_e32 v14, v0
	v_mov_b32_e32 v15, v0
	v_mov_b32_e32 v24, v0
	v_mov_b32_e32 v25, v0
	v_mov_b32_e32 v26, v0
	v_mov_b32_e32 v27, v0
	v_mov_b32_e32 v28, v0
	v_mov_b32_e32 v29, v0
	v_mov_b32_e32 v30, v0
	v_mov_b32_e32 v31, v0
	v_mov_b32_e32 v40, v0
	v_mov_b32_e32 v41, v0
	v_mov_b32_e32 v42, v0
	v_mov_b32_e32 v43, v0
	v_mov_b32_e32 v44, v0
	v_mov_b32_e32 v45, v0
	v_mov_b32_e32 v46, v0
	v_mov_b32_e32 v47, v0
	v_mov_b32_e32 v56, v0
	v_mov_b32_e32 v57, v0
	v_mov_b32_e32 v58, v0
	v_mov_b32_e32 v59, v0
	v_mov_b32_e32 v60, v0
	v_mov_b32_e32 v61, v0
	v_mov_b32_e32 v62, v0
	v_mov_b32_e32 v63, v0
	v_mov_b32_e32 v64, v0
	v_mov_b32_e32 v65, v0
	v_mov_b32_e32 v66, v0
	v_mov_b32_e32 v67, v0
	v_mov_b32_e32 v68, v0
	v_mov_b32_e32 v69, v0
	v_mov_b32_e32 v70, v0
	v_mov_b32_e32 v71, v0
	v_mov_b32_e32 v80, v0
	v_mov_b32_e32 v81, v0
	v_mov_b32_e32 v82, v0
	v_mov_b32_e32 v83, v0
	v_mov_b32_e32 v84, v0
	v_mov_b32_e32 v85, v0
	v_mov_b32_e32 v86, v0
	v_mov_b32_e32 v87, v0
	v_mov_b32_e32 v96, v0
	v_mov_b32_e32 v97, v0
	v_mov_b32_e32 v98, v0
	v_mov_b32_e32 v99, v0
	v_mov_b32_e32 v100, v0
	v_mov_b32_e32 v101, v0
	v_mov_b32_e32 v102, v0
	v_mov_b32_e32 v103, v0
	v_mov_b32_e32 v112, v0
	v_mov_b32_e32 v113, v0
	v_mov_b32_e32 v114, v0
	v_mov_b32_e32 v115, v0
	v_mov_b32_e32 v116, v0
	v_mov_b32_e32 v117, v0
	v_mov_b32_e32 v118, v0
	v_mov_b32_e32 v119, v0
	v_mov_b32_e32 v72, v0
	v_mov_b32_e32 v73, v0
	v_mov_b32_e32 v74, v0
	v_mov_b32_e32 v75, v0
	v_mov_b32_e32 v76, v0
	v_mov_b32_e32 v77, v0
	v_mov_b32_e32 v78, v0
	v_mov_b32_e32 v79, v0
	v_mov_b32_e32 v88, v0
	v_mov_b32_e32 v89, v0
	v_mov_b32_e32 v90, v0
	v_mov_b32_e32 v91, v0
	v_mov_b32_e32 v92, v0
	v_mov_b32_e32 v93, v0
	v_mov_b32_e32 v94, v0
	v_mov_b32_e32 v95, v0
	v_mov_b32_e32 v104, v0
	v_mov_b32_e32 v105, v0
	v_mov_b32_e32 v106, v0
	v_mov_b32_e32 v107, v0
	v_mov_b32_e32 v108, v0
	v_mov_b32_e32 v109, v0
	v_mov_b32_e32 v110, v0
	v_mov_b32_e32 v111, v0
	v_mov_b32_e32 v120, v0
	v_mov_b32_e32 v121, v0
	v_mov_b32_e32 v122, v0
	v_mov_b32_e32 v123, v0
	v_mov_b32_e32 v124, v0
	v_mov_b32_e32 v125, v0
	v_mov_b32_e32 v126, v0
	v_mov_b32_e32 v127, v0
	s_waitcnt vmcnt(0)
	.p2align	6

; template <class Epi>
; __device__ __forceinline__ void gemm_phase(LAS unsigned char* lds, const Gemm g, const StaticOrder& S, const Epi& E) {
;     ...
;         const bool has_next = S.next(ui + 1, nxt);
;         const char* nA = has_next ? (const char*)g.A + (size_t)nxt.pm * tstep : cA; const char* nB = has_next ? (const char*)g.Bt + (size_t)nxt.pn * tstep : cB;
;         for (int t = 0; t < nt; t += 2) {
;             const bool last = (t == nt - 2);
;             const char* a1 = cA + (size_t)(t + 1) * kstep;
;             const char* a2 = last ? nA : cA + (size_t)(t + 2) * kstep; const char* b2 = last ? nB : cB + (size_t)(t + 2) * kstep;
;     ...
; #pragma unroll
;         for (int a = 0; a < 2; ++a)
; #pragma unroll
;             for (int b = 0; b < 2; ++b)
; #pragma unroll
;                 for (int m = 0; m < 4; ++m)
; #pragma unroll
;                     for (int n = 0; n < 2; ++n) acc[a][b][m][n] = (f32x4){0.f, 0.f, 0.f, 0.f};
.LBB0_1219:
	s_ashr_i32 s13, s12, 31
	v_cmp_lt_i64_e32 vcc, s[14:15], v[150:151]
	s_lshl_b64 s[14:15], s[12:13], 20
	s_add_u32 s14, s34, s14
	s_addc_u32 s15, s35, s15
	s_and_b64 s[16:17], vcc, exec
	s_cselect_b32 s13, s15, s23
	s_cselect_b32 s19, s14, s22
	s_ashr_i32 s11, s10, 31
	s_lshl_b64 s[16:17], s[10:11], 20
	s_add_u32 s16, s37, s16
	s_addc_u32 s17, s38, s17
	s_and_b64 s[30:31], vcc, exec
	s_cselect_b32 s11, s17, s25
	s_cselect_b32 s64, s16, s24
	s_add_u32 s22, s22, 0x80080
	s_addc_u32 s23, s23, 0
	s_add_u32 s65, s24, 0x100
	v_mov_b32_e32 v0, 0
	s_addc_u32 s66, s25, 0
	s_mov_b32 s67, -2
	s_waitcnt lgkmcnt(0)
	v_mov_b32_e32 v1, v0
	v_mov_b32_e32 v2, v0
	v_mov_b32_e32 v3, v0
	v_mov_b32_e32 v4, v0
	v_mov_b32_e32 v5, v0
	v_mov_b32_e32 v6, v0
	v_mov_b32_e32 v7, v0
	v_mov_b32_e32 v16, v0
	v_mov_b32_e32 v17, v0
	v_mov_b32_e32 v18, v0
	v_mov_b32_e32 v19, v0
	v_mov_b32_e32 v20, v0
	v_mov_b32_e32 v21, v0
	v_mov_b32_e32 v22, v0
	v_mov_b32_e32 v23, v0
	v_mov_b32_e32 v32, v0
	v_mov_b32_e32 v33, v0
	v_mov_b32_e32 v34, v0
	v_mov_b32_e32 v35, v0
	v_mov_b32_e32 v36, v0
	v_mov_b32_e32 v37, v0
	v_mov_b32_e32 v38, v0
	v_mov_b32_e32 v39, v0
	v_mov_b32_e32 v48, v0
	v_mov_b32_e32 v49, v0
	v_mov_b32_e32 v50, v0
	v_mov_b32_e32 v51, v0
	v_mov_b32_e32 v52, v0
	v_mov_b32_e32 v53, v0
	v_mov_b32_e32 v54, v0
	v_mov_b32_e32 v55, v0
	v_mov_b32_e32 v8, v0
	v_mov_b32_e32 v9, v0
	v_mov_b32_e32 v10, v0
	v_mov_b32_e32 v11, v0
	v_mov_b32_e32 v12, v0
	v_mov_b32_e32 v13, v0
	v_mov_b32_e32 v14, v0
	v_mov_b32_e32 v15, v0
	v_mov_b32_e32 v24, v0
	v_mov_b32_e32 v25, v0
	v_mov_b32_e32 v26, v0
	v_mov_b32_e32 v27, v0
	v_mov_b32_e32 v28, v0
	v_mov_b32_e32 v29, v0
	v_mov_b32_e32 v30, v0
	v_mov_b32_e32 v31, v0
	v_mov_b32_e32 v40, v0
	v_mov_b32_e32 v41, v0
	v_mov_b32_e32 v42, v0
	v_mov_b32_e32 v43, v0
	v_mov_b32_e32 v44, v0
	v_mov_b32_e32 v45, v0
	v_mov_b32_e32 v46, v0
	v_mov_b32_e32 v47, v0
	v_mov_b32_e32 v56, v0
	v_mov_b32_e32 v57, v0
	v_mov_b32_e32 v58, v0
	v_mov_b32_e32 v59, v0
	v_mov_b32_e32 v60, v0
	v_mov_b32_e32 v61, v0
	v_mov_b32_e32 v62, v0
	v_mov_b32_e32 v63, v0
	v_mov_b32_e32 v64, v0
	v_mov_b32_e32 v65, v0
	v_mov_b32_e32 v66, v0
	v_mov_b32_e32 v67, v0
	v_mov_b32_e32 v68, v0
	v_mov_b32_e32 v69, v0
	v_mov_b32_e32 v70, v0
	v_mov_b32_e32 v71, v0
	v_mov_b32_e32 v80, v0
	v_mov_b32_e32 v81, v0
	v_mov_b32_e32 v82, v0
	v_mov_b32_e32 v83, v0
	v_mov_b32_e32 v84, v0
	v_mov_b32_e32 v85, v0
	v_mov_b32_e32 v86, v0
	v_mov_b32_e32 v87, v0
	v_mov_b32_e32 v96, v0
	v_mov_b32_e32 v97, v0
	v_mov_b32_e32 v98, v0
	v_mov_b32_e32 v99, v0
	v_mov_b32_e32 v100, v0
	v_mov_b32_e32 v101, v0
	v_mov_b32_e32 v102, v0
	v_mov_b32_e32 v103, v0
	v_mov_b32_e32 v112, v0
	v_mov_b32_e32 v113, v0
	v_mov_b32_e32 v114, v0
	v_mov_b32_e32 v115, v0
	v_mov_b32_e32 v116, v0
	v_mov_b32_e32 v117, v0
	v_mov_b32_e32 v118, v0
	v_mov_b32_e32 v119, v0
	v_mov_b32_e32 v72, v0
	v_mov_b32_e32 v73, v0
	v_mov_b32_e32 v74, v0
	v_mov_b32_e32 v75, v0
	v_mov_b32_e32 v76, v0
	v_mov_b32_e32 v77, v0
	v_mov_b32_e32 v78, v0
	v_mov_b32_e32 v79, v0
	v_mov_b32_e32 v88, v0
	v_mov_b32_e32 v89, v0
	v_mov_b32_e32 v90, v0
	v_mov_b32_e32 v91, v0
	v_mov_b32_e32 v92, v0
	v_mov_b32_e32 v93, v0
	v_mov_b32_e32 v94, v0
	v_mov_b32_e32 v95, v0
	v_mov_b32_e32 v104, v0
	v_mov_b32_e32 v105, v0
	v_mov_b32_e32 v106, v0
	v_mov_b32_e32 v107, v0
	v_mov_b32_e32 v108, v0
	v_mov_b32_e32 v109, v0
	v_mov_b32_e32 v110, v0
	v_mov_b32_e32 v111, v0
	v_mov_b32_e32 v120, v0
	v_mov_b32_e32 v121, v0
	v_mov_b32_e32 v122, v0
	v_mov_b32_e32 v123, v0
	v_mov_b32_e32 v124, v0
	v_mov_b32_e32 v125, v0
	v_mov_b32_e32 v126, v0
	v_mov_b32_e32 v127, v0
	.p2align	6

; template <class Epi>
; __device__ __forceinline__ void gemm_phase(LAS unsigned char* lds, const Gemm g, const StaticOrder& S, const Epi& E) {
;     ...
;         const bool has_next = S.next(ui + 1, nxt);
;         const char* nA = has_next ? (const char*)g.A + (size_t)nxt.pm * tstep : cA; const char* nB = has_next ? (const char*)g.Bt + (size_t)nxt.pn * tstep : cB;
;         for (int t = 0; t < nt; t += 2) {
;             const bool last = (t == nt - 2);
;             const char* a1 = cA + (size_t)(t + 1) * kstep;
;             const char* a2 = last ? nA : cA + (size_t)(t + 2) * kstep; const char* b2 = last ? nB : cB + (size_t)(t + 2) * kstep;
;     ...
; #pragma unroll
;         for (int a = 0; a < 2; ++a)
; #pragma unroll
;             for (int b = 0; b < 2; ++b)
; #pragma unroll
;                 for (int m = 0; m < 4; ++m)
; #pragma unroll
;                     for (int n = 0; n < 2; ++n) acc[a][b][m][n] = (f32x4){0.f, 0.f, 0.f, 0.f};
.LBB0_1305:
	s_ashr_i32 s9, s8, 31
	v_cmp_lt_i64_e32 vcc, s[10:11], v[142:143]
	s_lshl_b64 s[10:11], s[8:9], 20
	s_add_u32 s10, s23, s10
	s_addc_u32 s11, s24, s11
	s_and_b64 s[12:13], vcc, exec
	s_cselect_b32 s9, s11, s17
	s_cselect_b32 s61, s10, s16
	s_ashr_i32 s7, s6, 31
	s_lshl_b64 s[12:13], s[6:7], 20
	s_add_u32 s12, s25, s12
	s_addc_u32 s13, s30, s13
	s_and_b64 s[20:21], vcc, exec
	s_cselect_b32 s7, s13, s19
	s_cselect_b32 s62, s12, s18
	s_add_u32 s16, s16, 0x80080
	s_addc_u32 s17, s17, 0
	s_add_u32 s63, s18, 0x100
	v_mov_b32_e32 v0, 0
	s_addc_u32 s64, s19, 0
	s_mov_b32 s65, -2
	v_mov_b32_e32 v1, v0
	v_mov_b32_e32 v2, v0
	v_mov_b32_e32 v3, v0
	v_mov_b32_e32 v8, v0
	v_mov_b32_e32 v9, v0
	v_mov_b32_e32 v10, v0
	v_mov_b32_e32 v11, v0
	v_mov_b32_e32 v16, v0
	v_mov_b32_e32 v17, v0
	v_mov_b32_e32 v18, v0
	v_mov_b32_e32 v19, v0
	v_mov_b32_e32 v24, v0
	v_mov_b32_e32 v25, v0
	v_mov_b32_e32 v26, v0
	v_mov_b32_e32 v27, v0
	v_mov_b32_e32 v32, v0
	v_mov_b32_e32 v33, v0
	v_mov_b32_e32 v34, v0
	v_mov_b32_e32 v35, v0
	v_mov_b32_e32 v40, v0
	v_mov_b32_e32 v41, v0
	v_mov_b32_e32 v42, v0
	v_mov_b32_e32 v43, v0
	v_mov_b32_e32 v48, v0
	v_mov_b32_e32 v49, v0
	v_mov_b32_e32 v50, v0
	v_mov_b32_e32 v51, v0
	v_mov_b32_e32 v56, v0
	v_mov_b32_e32 v57, v0
	v_mov_b32_e32 v58, v0
	v_mov_b32_e32 v59, v0
	v_mov_b32_e32 v4, v0
	v_mov_b32_e32 v5, v0
	v_mov_b32_e32 v6, v0
	v_mov_b32_e32 v7, v0
	v_mov_b32_e32 v12, v0
	v_mov_b32_e32 v13, v0
	v_mov_b32_e32 v14, v0
	v_mov_b32_e32 v15, v0
	v_mov_b32_e32 v20, v0
	v_mov_b32_e32 v21, v0
	v_mov_b32_e32 v22, v0
	v_mov_b32_e32 v23, v0
	v_mov_b32_e32 v28, v0
	v_mov_b32_e32 v29, v0
	v_mov_b32_e32 v30, v0
	v_mov_b32_e32 v31, v0
	v_mov_b32_e32 v36, v0
	v_mov_b32_e32 v37, v0
	v_mov_b32_e32 v38, v0
	v_mov_b32_e32 v39, v0
	v_mov_b32_e32 v44, v0
	v_mov_b32_e32 v45, v0
	v_mov_b32_e32 v46, v0
	v_mov_b32_e32 v47, v0
	v_mov_b32_e32 v52, v0
	v_mov_b32_e32 v53, v0
	v_mov_b32_e32 v54, v0
	v_mov_b32_e32 v55, v0
	v_mov_b32_e32 v60, v0
	v_mov_b32_e32 v61, v0
	v_mov_b32_e32 v62, v0
	v_mov_b32_e32 v63, v0
	v_mov_b32_e32 v64, v0
	v_mov_b32_e32 v65, v0
	v_mov_b32_e32 v66, v0
	v_mov_b32_e32 v67, v0
	v_mov_b32_e32 v72, v0
	v_mov_b32_e32 v73, v0
	v_mov_b32_e32 v74, v0
	v_mov_b32_e32 v75, v0
	v_mov_b32_e32 v80, v0
	v_mov_b32_e32 v81, v0
	v_mov_b32_e32 v82, v0
	v_mov_b32_e32 v83, v0
	v_mov_b32_e32 v88, v0
	v_mov_b32_e32 v89, v0
	v_mov_b32_e32 v90, v0
	v_mov_b32_e32 v91, v0
	v_mov_b32_e32 v96, v0
	v_mov_b32_e32 v97, v0
	v_mov_b32_e32 v98, v0
	v_mov_b32_e32 v99, v0
	v_mov_b32_e32 v104, v0
	v_mov_b32_e32 v105, v0
	v_mov_b32_e32 v106, v0
	v_mov_b32_e32 v107, v0
	v_mov_b32_e32 v112, v0
	v_mov_b32_e32 v113, v0
	v_mov_b32_e32 v114, v0
	v_mov_b32_e32 v115, v0
	v_mov_b32_e32 v120, v0
	v_mov_b32_e32 v121, v0
	v_mov_b32_e32 v122, v0
	v_mov_b32_e32 v123, v0
	v_mov_b32_e32 v68, v0
	v_mov_b32_e32 v69, v0
	v_mov_b32_e32 v70, v0
	v_mov_b32_e32 v71, v0
	v_mov_b32_e32 v76, v0
	v_mov_b32_e32 v77, v0
	v_mov_b32_e32 v78, v0
	v_mov_b32_e32 v79, v0
	v_mov_b32_e32 v84, v0
	v_mov_b32_e32 v85, v0
	v_mov_b32_e32 v86, v0
	v_mov_b32_e32 v87, v0
	v_mov_b32_e32 v92, v0
	v_mov_b32_e32 v93, v0
	v_mov_b32_e32 v94, v0
	v_mov_b32_e32 v95, v0
	v_mov_b32_e32 v100, v0
	v_mov_b32_e32 v101, v0
	v_mov_b32_e32 v102, v0
	v_mov_b32_e32 v103, v0
	v_mov_b32_e32 v108, v0
	v_mov_b32_e32 v109, v0
	v_mov_b32_e32 v110, v0
	v_mov_b32_e32 v111, v0
	v_mov_b32_e32 v116, v0
	v_mov_b32_e32 v117, v0
	v_mov_b32_e32 v118, v0
	v_mov_b32_e32 v119, v0
	v_mov_b32_e32 v124, v0
	v_mov_b32_e32 v125, v0
	v_mov_b32_e32 v126, v0
	v_mov_b32_e32 v127, v0
	.p2align	6

; template <class Epi>
; __device__ __forceinline__ void gemm_phase(LAS unsigned char* lds, const Gemm g, const StaticOrder& S, const Epi& E) {
;     ...
;         for (int t = 0; t < nt; t += 2) {
;             const bool last = (t == nt - 2);
;             const char* a1 = cA + (size_t)(t + 1) * kstep;
;             const char* a2 = last ? nA : cA + (size_t)(t + 2) * kstep; const char* b2 = last ? nB : cB + (size_t)(t + 2) * kstep;
;             const char* a3 = a2 + kstep; const char* b3 = b2 + kstep;
;     ...
; #pragma unroll
;         for (int a = 0; a < 2; ++a)
; #pragma unroll
;             for (int b = 0; b < 2; ++b)
; #pragma unroll
;                 for (int m = 0; m < 4; ++m)
; #pragma unroll
;                     for (int n = 0; n < 2; ++n) acc[a][b][m][n] = (f32x4){0.f, 0.f, 0.f, 0.f};
;         cur = nxt; cA = nA; cB = nB; ++ui;
.LBB0_1410:
	s_add_u32 s14, s14, 0x158080
	s_addc_u32 s15, s15, 0
	s_add_u32 s61, s16, 0x100
	v_mov_b32_e32 v0, 0
	s_addc_u32 s62, s17, 0
	s_mov_b32 s63, -2
	s_waitcnt lgkmcnt(0)
	v_mov_b32_e32 v1, v0
	v_mov_b32_e32 v2, v0
	v_mov_b32_e32 v3, v0
	v_mov_b32_e32 v4, v0
	v_mov_b32_e32 v5, v0
	v_mov_b32_e32 v6, v0
	v_mov_b32_e32 v7, v0
	v_mov_b32_e32 v16, v0
	v_mov_b32_e32 v17, v0
	v_mov_b32_e32 v18, v0
	v_mov_b32_e32 v19, v0
	v_mov_b32_e32 v20, v0
	v_mov_b32_e32 v21, v0
	v_mov_b32_e32 v22, v0
	v_mov_b32_e32 v23, v0
	v_mov_b32_e32 v32, v0
	v_mov_b32_e32 v33, v0
	v_mov_b32_e32 v34, v0
	v_mov_b32_e32 v35, v0
	v_mov_b32_e32 v36, v0
	v_mov_b32_e32 v37, v0
	v_mov_b32_e32 v38, v0
	v_mov_b32_e32 v39, v0
	v_mov_b32_e32 v48, v0
	v_mov_b32_e32 v49, v0
	v_mov_b32_e32 v50, v0
	v_mov_b32_e32 v51, v0
	v_mov_b32_e32 v52, v0
	v_mov_b32_e32 v53, v0
	v_mov_b32_e32 v54, v0
	v_mov_b32_e32 v55, v0
	v_mov_b32_e32 v8, v0
	v_mov_b32_e32 v9, v0
	v_mov_b32_e32 v10, v0
	v_mov_b32_e32 v11, v0
	v_mov_b32_e32 v12, v0
	v_mov_b32_e32 v13, v0
	v_mov_b32_e32 v14, v0
	v_mov_b32_e32 v15, v0
	v_mov_b32_e32 v24, v0
	v_mov_b32_e32 v25, v0
	v_mov_b32_e32 v26, v0
	v_mov_b32_e32 v27, v0
	v_mov_b32_e32 v28, v0
	v_mov_b32_e32 v29, v0
	v_mov_b32_e32 v30, v0
	v_mov_b32_e32 v31, v0
	v_mov_b32_e32 v40, v0
	v_mov_b32_e32 v41, v0
	v_mov_b32_e32 v42, v0
	v_mov_b32_e32 v43, v0
	v_mov_b32_e32 v44, v0
	v_mov_b32_e32 v45, v0
	v_mov_b32_e32 v46, v0
	v_mov_b32_e32 v47, v0
	v_mov_b32_e32 v56, v0
	v_mov_b32_e32 v57, v0
	v_mov_b32_e32 v58, v0
	v_mov_b32_e32 v59, v0
	v_mov_b32_e32 v60, v0
	v_mov_b32_e32 v61, v0
	v_mov_b32_e32 v62, v0
	v_mov_b32_e32 v63, v0
	v_mov_b32_e32 v64, v0
	v_mov_b32_e32 v65, v0
	v_mov_b32_e32 v66, v0
	v_mov_b32_e32 v67, v0
	v_mov_b32_e32 v68, v0
	v_mov_b32_e32 v69, v0
	v_mov_b32_e32 v70, v0
	v_mov_b32_e32 v71, v0
	v_mov_b32_e32 v80, v0
	v_mov_b32_e32 v81, v0
	v_mov_b32_e32 v82, v0
	v_mov_b32_e32 v83, v0
	v_mov_b32_e32 v84, v0
	v_mov_b32_e32 v85, v0
	v_mov_b32_e32 v86, v0
	v_mov_b32_e32 v87, v0
	v_mov_b32_e32 v96, v0
	v_mov_b32_e32 v97, v0
	v_mov_b32_e32 v98, v0
	v_mov_b32_e32 v99, v0
	v_mov_b32_e32 v100, v0
	v_mov_b32_e32 v101, v0
	v_mov_b32_e32 v102, v0
	v_mov_b32_e32 v103, v0
	v_mov_b32_e32 v112, v0
	v_mov_b32_e32 v113, v0
	v_mov_b32_e32 v114, v0
	v_mov_b32_e32 v115, v0
	v_mov_b32_e32 v116, v0
	v_mov_b32_e32 v117, v0
	v_mov_b32_e32 v118, v0
	v_mov_b32_e32 v119, v0
	v_mov_b32_e32 v72, v0
	v_mov_b32_e32 v73, v0
	v_mov_b32_e32 v74, v0
	v_mov_b32_e32 v75, v0
	v_mov_b32_e32 v76, v0
	v_mov_b32_e32 v77, v0
	v_mov_b32_e32 v78, v0
	v_mov_b32_e32 v79, v0
	v_mov_b32_e32 v88, v0
	v_mov_b32_e32 v89, v0
	v_mov_b32_e32 v90, v0
	v_mov_b32_e32 v91, v0
	v_mov_b32_e32 v92, v0
	v_mov_b32_e32 v93, v0
	v_mov_b32_e32 v94, v0
	v_mov_b32_e32 v95, v0
	v_mov_b32_e32 v104, v0
	v_mov_b32_e32 v105, v0
	v_mov_b32_e32 v106, v0
	v_mov_b32_e32 v107, v0
	v_mov_b32_e32 v108, v0
	v_mov_b32_e32 v109, v0
	v_mov_b32_e32 v110, v0
	v_mov_b32_e32 v111, v0
	v_mov_b32_e32 v120, v0
	v_mov_b32_e32 v121, v0
	v_mov_b32_e32 v122, v0
	v_mov_b32_e32 v123, v0
	v_mov_b32_e32 v124, v0
	v_mov_b32_e32 v125, v0
	v_mov_b32_e32 v126, v0
	v_mov_b32_e32 v127, v0
	.p2align	6

; template <class Epi>
; __device__ __forceinline__ void gemm_phase(LAS unsigned char* lds, const Gemm g, const StaticOrder& S, const Epi& E) {
;     ...
;         const bool has_next = S.next(ui + 1, nxt);
;         const char* nA = has_next ? (const char*)g.A + (size_t)nxt.pm * tstep : cA; const char* nB = has_next ? (const char*)g.Bt + (size_t)nxt.pn * tstep : cB;
;         for (int t = 0; t < nt; t += 2) {
;             const bool last = (t == nt - 2);
;             const char* a1 = cA + (size_t)(t + 1) * kstep;
;             const char* a2 = last ? nA : cA + (size_t)(t + 2) * kstep; const char* b2 = last ? nB : cB + (size_t)(t + 2) * kstep;
;     ...
; #pragma unroll
;         for (int a = 0; a < 2; ++a)
; #pragma unroll
;             for (int b = 0; b < 2; ++b)
; #pragma unroll
;                 for (int m = 0; m < 4; ++m)
; #pragma unroll
;                     for (int n = 0; n < 2; ++n) acc[a][b][m][n] = (f32x4){0.f, 0.f, 0.f, 0.f};
.LBB0_1795:
	s_ashr_i32 s37, s36, 31
	s_lshl_b64 s[8:9], s[36:37], 20
	s_add_u32 s38, s58, s8
	v_cmp_lt_i64_e64 s[2:3], s[2:3], v[146:147]
	s_addc_u32 s39, s59, s9
	s_and_b64 s[8:9], s[2:3], exec
	s_cselect_b32 s1, s39, s7
	s_cselect_b32 s5, s38, s6
	s_ashr_i32 s35, s34, 31
	s_lshl_b64 s[8:9], s[34:35], 20
	s_add_u32 s40, s60, s8
	s_addc_u32 s41, s61, s9
	s_and_b64 s[8:9], s[2:3], exec
	s_cselect_b32 s12, s41, s11
	s_cselect_b32 s13, s40, s10
	s_add_u32 s6, s6, 0x80080
	s_addc_u32 s7, s7, 0
	s_add_u32 s33, s10, 0x100
	v_mov_b32_e32 v8, 0
	s_addc_u32 s35, s11, 0
	s_mov_b32 s37, -2
	v_mov_b32_e32 v9, v8
	v_mov_b32_e32 v10, v8
	v_mov_b32_e32 v11, v8
	v_mov_b32_e32 v12, v8
	v_mov_b32_e32 v13, v8
	v_mov_b32_e32 v14, v8
	v_mov_b32_e32 v15, v8
	v_mov_b32_e32 v24, v8
	v_mov_b32_e32 v25, v8
	v_mov_b32_e32 v26, v8
	v_mov_b32_e32 v27, v8
	v_mov_b32_e32 v28, v8
	v_mov_b32_e32 v29, v8
	v_mov_b32_e32 v30, v8
	v_mov_b32_e32 v31, v8
	v_mov_b32_e32 v40, v8
	v_mov_b32_e32 v41, v8
	v_mov_b32_e32 v42, v8
	v_mov_b32_e32 v43, v8
	v_mov_b32_e32 v44, v8
	v_mov_b32_e32 v45, v8
	v_mov_b32_e32 v46, v8
	v_mov_b32_e32 v47, v8
	v_mov_b32_e32 v56, v8
	v_mov_b32_e32 v57, v8
	v_mov_b32_e32 v58, v8
	v_mov_b32_e32 v59, v8
	v_mov_b32_e32 v60, v8
	v_mov_b32_e32 v61, v8
	v_mov_b32_e32 v62, v8
	v_mov_b32_e32 v63, v8
	v_mov_b32_e32 v0, v8
	v_mov_b32_e32 v1, v8
	v_mov_b32_e32 v2, v8
	v_mov_b32_e32 v3, v8
	v_mov_b32_e32 v4, v8
	v_mov_b32_e32 v5, v8
	v_mov_b32_e32 v6, v8
	v_mov_b32_e32 v7, v8
	v_mov_b32_e32 v16, v8
	v_mov_b32_e32 v17, v8
	v_mov_b32_e32 v18, v8
	v_mov_b32_e32 v19, v8
	v_mov_b32_e32 v20, v8
	v_mov_b32_e32 v21, v8
	v_mov_b32_e32 v22, v8
	v_mov_b32_e32 v23, v8
	v_mov_b32_e32 v32, v8
	v_mov_b32_e32 v33, v8
	v_mov_b32_e32 v34, v8
	v_mov_b32_e32 v35, v8
	v_mov_b32_e32 v36, v8
	v_mov_b32_e32 v37, v8
	v_mov_b32_e32 v38, v8
	v_mov_b32_e32 v39, v8
	v_mov_b32_e32 v48, v8
	v_mov_b32_e32 v49, v8
	v_mov_b32_e32 v50, v8
	v_mov_b32_e32 v51, v8
	v_mov_b32_e32 v52, v8
	v_mov_b32_e32 v53, v8
	v_mov_b32_e32 v54, v8
	v_mov_b32_e32 v55, v8
	v_mov_b32_e32 v72, v8
	v_mov_b32_e32 v73, v8
	v_mov_b32_e32 v74, v8
	v_mov_b32_e32 v75, v8
	v_mov_b32_e32 v76, v8
	v_mov_b32_e32 v77, v8
	v_mov_b32_e32 v78, v8
	v_mov_b32_e32 v79, v8
	v_mov_b32_e32 v88, v8
	v_mov_b32_e32 v89, v8
	v_mov_b32_e32 v90, v8
	v_mov_b32_e32 v91, v8
	v_mov_b32_e32 v92, v8
	v_mov_b32_e32 v93, v8
	v_mov_b32_e32 v94, v8
	v_mov_b32_e32 v95, v8
	v_mov_b32_e32 v104, v8
	v_mov_b32_e32 v105, v8
	v_mov_b32_e32 v106, v8
	v_mov_b32_e32 v107, v8
	v_mov_b32_e32 v108, v8
	v_mov_b32_e32 v109, v8
	v_mov_b32_e32 v110, v8
	v_mov_b32_e32 v111, v8
	v_mov_b32_e32 v120, v8
	v_mov_b32_e32 v121, v8
	v_mov_b32_e32 v122, v8
	v_mov_b32_e32 v123, v8
	v_mov_b32_e32 v124, v8
	v_mov_b32_e32 v125, v8
	v_mov_b32_e32 v126, v8
	v_mov_b32_e32 v127, v8
	v_mov_b32_e32 v64, v8
	v_mov_b32_e32 v65, v8
	v_mov_b32_e32 v66, v8
	v_mov_b32_e32 v67, v8
	v_mov_b32_e32 v68, v8
	v_mov_b32_e32 v69, v8
	v_mov_b32_e32 v70, v8
	v_mov_b32_e32 v71, v8
	v_mov_b32_e32 v80, v8
	v_mov_b32_e32 v81, v8
	v_mov_b32_e32 v82, v8
	v_mov_b32_e32 v83, v8
	v_mov_b32_e32 v84, v8
	v_mov_b32_e32 v85, v8
	v_mov_b32_e32 v86, v8
	v_mov_b32_e32 v87, v8
	v_mov_b32_e32 v96, v8
	v_mov_b32_e32 v97, v8
	v_mov_b32_e32 v98, v8
	v_mov_b32_e32 v99, v8
	v_mov_b32_e32 v100, v8
	v_mov_b32_e32 v101, v8
	v_mov_b32_e32 v102, v8
	v_mov_b32_e32 v103, v8
	v_mov_b32_e32 v112, v8
	v_mov_b32_e32 v113, v8
	v_mov_b32_e32 v114, v8
	v_mov_b32_e32 v115, v8
	v_mov_b32_e32 v116, v8
	v_mov_b32_e32 v117, v8
	v_mov_b32_e32 v118, v8
	v_mov_b32_e32 v119, v8
	.p2align	6

; template <class Epi>
; __device__ __forceinline__ void gemm_phase(LAS unsigned char* lds, const Gemm g, const StaticOrder& S, const Epi& E) {
;     ...
;         const bool has_next = S.next(ui + 1, nxt);
;         const char* nA = has_next ? (const char*)g.A + (size_t)nxt.pm * tstep : cA; const char* nB = has_next ? (const char*)g.Bt + (size_t)nxt.pn * tstep : cB;
;         for (int t = 0; t < nt; t += 2) {
;             const bool last = (t == nt - 2);
;             const char* a1 = cA + (size_t)(t + 1) * kstep;
;             const char* a2 = last ? nA : cA + (size_t)(t + 2) * kstep; const char* b2 = last ? nB : cB + (size_t)(t + 2) * kstep;
;             const char* a3 = a2 + kstep; const char* b3 = b2 + kstep;
;     ...
; #pragma unroll
;         for (int a = 0; a < 2; ++a)
; #pragma unroll
;             for (int b = 0; b < 2; ++b)
; #pragma unroll
;                 for (int m = 0; m < 4; ++m)
; #pragma unroll
;                     for (int n = 0; n < 2; ++n) acc[a][b][m][n] = (f32x4){0.f, 0.f, 0.f, 0.f};
;         cur = nxt; cA = nA; cB = nB; ++ui;
.LBB0_2459:
	s_ashr_i32 s13, s12, 31
	v_cmp_lt_i64_e32 vcc, s[14:15], v[148:149]
	s_lshl_b64 s[14:15], s[12:13], 20
	s_add_u32 s14, s36, s14
	s_addc_u32 s15, s37, s15
	s_and_b64 s[16:17], vcc, exec
	s_cselect_b32 s13, s15, s23
	s_cselect_b32 s19, s14, s22
	s_ashr_i32 s11, s10, 31
	s_lshl_b64 s[16:17], s[10:11], 20
	s_add_u32 s16, s34, s16
	s_addc_u32 s17, s35, s17
	s_and_b64 s[30:31], vcc, exec
	s_cselect_b32 s11, s17, s25
	s_cselect_b32 s58, s16, s24
	s_add_u32 s22, s22, 0x80080
	s_addc_u32 s23, s23, 0
	s_add_u32 s59, s24, 0x100
	v_mov_b32_e32 v0, 0
	s_addc_u32 s60, s25, 0
	s_mov_b32 s61, -2
	s_waitcnt lgkmcnt(0)
	v_mov_b32_e32 v1, v0
	v_mov_b32_e32 v2, v0
	v_mov_b32_e32 v3, v0
	v_mov_b32_e32 v4, v0
	v_mov_b32_e32 v5, v0
	v_mov_b32_e32 v6, v0
	v_mov_b32_e32 v7, v0
	v_mov_b32_e32 v16, v0
	v_mov_b32_e32 v17, v0
	v_mov_b32_e32 v18, v0
	v_mov_b32_e32 v19, v0
	v_mov_b32_e32 v20, v0
	v_mov_b32_e32 v21, v0
	v_mov_b32_e32 v22, v0
	v_mov_b32_e32 v23, v0
	v_mov_b32_e32 v32, v0
	v_mov_b32_e32 v33, v0
	v_mov_b32_e32 v34, v0
	v_mov_b32_e32 v35, v0
	v_mov_b32_e32 v36, v0
	v_mov_b32_e32 v37, v0
	v_mov_b32_e32 v38, v0
	v_mov_b32_e32 v39, v0
	v_mov_b32_e32 v48, v0
	v_mov_b32_e32 v49, v0
	v_mov_b32_e32 v50, v0
	v_mov_b32_e32 v51, v0
	v_mov_b32_e32 v52, v0
	v_mov_b32_e32 v53, v0
	v_mov_b32_e32 v54, v0
	v_mov_b32_e32 v55, v0
	v_mov_b32_e32 v8, v0
	v_mov_b32_e32 v9, v0
	v_mov_b32_e32 v10, v0
	v_mov_b32_e32 v11, v0
	v_mov_b32_e32 v12, v0
	v_mov_b32_e32 v13, v0
	v_mov_b32_e32 v14, v0
	v_mov_b32_e32 v15, v0
	v_mov_b32_e32 v24, v0
	v_mov_b32_e32 v25, v0
	v_mov_b32_e32 v26, v0
	v_mov_b32_e32 v27, v0
	v_mov_b32_e32 v28, v0
	v_mov_b32_e32 v29, v0
	v_mov_b32_e32 v30, v0
	v_mov_b32_e32 v31, v0
	v_mov_b32_e32 v40, v0
	v_mov_b32_e32 v41, v0
	v_mov_b32_e32 v42, v0
	v_mov_b32_e32 v43, v0
	v_mov_b32_e32 v44, v0
	v_mov_b32_e32 v45, v0
	v_mov_b32_e32 v46, v0
	v_mov_b32_e32 v47, v0
	v_mov_b32_e32 v56, v0
	v_mov_b32_e32 v57, v0
	v_mov_b32_e32 v58, v0
	v_mov_b32_e32 v59, v0
	v_mov_b32_e32 v60, v0
	v_mov_b32_e32 v61, v0
	v_mov_b32_e32 v62, v0
	v_mov_b32_e32 v63, v0
	v_mov_b32_e32 v64, v0
	v_mov_b32_e32 v65, v0
	v_mov_b32_e32 v66, v0
	v_mov_b32_e32 v67, v0
	v_mov_b32_e32 v68, v0
	v_mov_b32_e32 v69, v0
	v_mov_b32_e32 v70, v0
	v_mov_b32_e32 v71, v0
	v_mov_b32_e32 v80, v0
	v_mov_b32_e32 v81, v0
	v_mov_b32_e32 v82, v0
	v_mov_b32_e32 v83, v0
	v_mov_b32_e32 v84, v0
	v_mov_b32_e32 v85, v0
	v_mov_b32_e32 v86, v0
	v_mov_b32_e32 v87, v0
	v_mov_b32_e32 v96, v0
	v_mov_b32_e32 v97, v0
	v_mov_b32_e32 v98, v0
	v_mov_b32_e32 v99, v0
	v_mov_b32_e32 v100, v0
	v_mov_b32_e32 v101, v0
	v_mov_b32_e32 v102, v0
	v_mov_b32_e32 v103, v0
	v_mov_b32_e32 v112, v0
	v_mov_b32_e32 v113, v0
	v_mov_b32_e32 v114, v0
	v_mov_b32_e32 v115, v0
	v_mov_b32_e32 v116, v0
	v_mov_b32_e32 v117, v0
	v_mov_b32_e32 v118, v0
	v_mov_b32_e32 v119, v0
	v_mov_b32_e32 v72, v0
	v_mov_b32_e32 v73, v0
	v_mov_b32_e32 v74, v0
	v_mov_b32_e32 v75, v0
	v_mov_b32_e32 v76, v0
	v_mov_b32_e32 v77, v0
	v_mov_b32_e32 v78, v0
	v_mov_b32_e32 v79, v0
	v_mov_b32_e32 v88, v0
	v_mov_b32_e32 v89, v0
	v_mov_b32_e32 v90, v0
	v_mov_b32_e32 v91, v0
	v_mov_b32_e32 v92, v0
	v_mov_b32_e32 v93, v0
	v_mov_b32_e32 v94, v0
	v_mov_b32_e32 v95, v0
	v_mov_b32_e32 v104, v0
	v_mov_b32_e32 v105, v0
	v_mov_b32_e32 v106, v0
	v_mov_b32_e32 v107, v0
	v_mov_b32_e32 v108, v0
	v_mov_b32_e32 v109, v0
	v_mov_b32_e32 v110, v0
	v_mov_b32_e32 v111, v0
	v_mov_b32_e32 v120, v0
	v_mov_b32_e32 v121, v0
	v_mov_b32_e32 v122, v0
	v_mov_b32_e32 v123, v0
	v_mov_b32_e32 v124, v0
	v_mov_b32_e32 v125, v0
	v_mov_b32_e32 v126, v0
	v_mov_b32_e32 v127, v0
	.p2align	6

; template <class Epi>
; __device__ __forceinline__ void gemm_phase(LAS unsigned char* lds, const Gemm g, const StaticOrder& S, const Epi& E) {
;     ...
;         const bool has_next = S.next(ui + 1, nxt);
;         const char* nA = has_next ? (const char*)g.A + (size_t)nxt.pm * tstep : cA; const char* nB = has_next ? (const char*)g.Bt + (size_t)nxt.pn * tstep : cB;
;         for (int t = 0; t < nt; t += 2) {
;             const bool last = (t == nt - 2);
;             const char* a1 = cA + (size_t)(t + 1) * kstep;
;             const char* a2 = last ? nA : cA + (size_t)(t + 2) * kstep; const char* b2 = last ? nB : cB + (size_t)(t + 2) * kstep;
;             const char* a3 = a2 + kstep; const char* b3 = b2 + kstep;
;     ...
; #pragma unroll
;         for (int a = 0; a < 2; ++a)
; #pragma unroll
;             for (int b = 0; b < 2; ++b)
; #pragma unroll
;                 for (int m = 0; m < 4; ++m)
; #pragma unroll
;                     for (int n = 0; n < 2; ++n) acc[a][b][m][n] = (f32x4){0.f, 0.f, 0.f, 0.f};
;         cur = nxt; cA = nA; cB = nB; ++ui;
.LBB0_2545:
	s_ashr_i32 s9, s8, 31
	v_cmp_lt_i64_e32 vcc, s[10:11], v[140:141]
	s_lshl_b64 s[10:11], s[8:9], 20
	s_add_u32 s10, s23, s10
	s_addc_u32 s11, s24, s11
	s_and_b64 s[12:13], vcc, exec
	s_cselect_b32 s9, s11, s17
	s_cselect_b32 s47, s10, s16
	s_ashr_i32 s7, s6, 31
	s_lshl_b64 s[12:13], s[6:7], 20
	s_add_u32 s12, s25, s12
	s_addc_u32 s13, s30, s13
	s_and_b64 s[20:21], vcc, exec
	s_cselect_b32 s7, s13, s19
	s_cselect_b32 s56, s12, s18
	s_add_u32 s16, s16, 0x80080
	s_addc_u32 s17, s17, 0
	s_add_u32 s57, s18, 0x100
	v_mov_b32_e32 v0, 0
	s_addc_u32 s58, s19, 0
	s_mov_b32 s59, -2
	v_mov_b32_e32 v1, v0
	v_mov_b32_e32 v2, v0
	v_mov_b32_e32 v3, v0
	v_mov_b32_e32 v8, v0
	v_mov_b32_e32 v9, v0
	v_mov_b32_e32 v10, v0
	v_mov_b32_e32 v11, v0
	v_mov_b32_e32 v16, v0
	v_mov_b32_e32 v17, v0
	v_mov_b32_e32 v18, v0
	v_mov_b32_e32 v19, v0
	v_mov_b32_e32 v24, v0
	v_mov_b32_e32 v25, v0
	v_mov_b32_e32 v26, v0
	v_mov_b32_e32 v27, v0
	v_mov_b32_e32 v32, v0
	v_mov_b32_e32 v33, v0
	v_mov_b32_e32 v34, v0
	v_mov_b32_e32 v35, v0
	v_mov_b32_e32 v40, v0
	v_mov_b32_e32 v41, v0
	v_mov_b32_e32 v42, v0
	v_mov_b32_e32 v43, v0
	v_mov_b32_e32 v48, v0
	v_mov_b32_e32 v49, v0
	v_mov_b32_e32 v50, v0
	v_mov_b32_e32 v51, v0
	v_mov_b32_e32 v56, v0
	v_mov_b32_e32 v57, v0
	v_mov_b32_e32 v58, v0
	v_mov_b32_e32 v59, v0
	v_mov_b32_e32 v4, v0
	v_mov_b32_e32 v5, v0
	v_mov_b32_e32 v6, v0
	v_mov_b32_e32 v7, v0
	v_mov_b32_e32 v12, v0
	v_mov_b32_e32 v13, v0
	v_mov_b32_e32 v14, v0
	v_mov_b32_e32 v15, v0
	v_mov_b32_e32 v20, v0
	v_mov_b32_e32 v21, v0
	v_mov_b32_e32 v22, v0
	v_mov_b32_e32 v23, v0
	v_mov_b32_e32 v28, v0
	v_mov_b32_e32 v29, v0
	v_mov_b32_e32 v30, v0
	v_mov_b32_e32 v31, v0
	v_mov_b32_e32 v36, v0
	v_mov_b32_e32 v37, v0
	v_mov_b32_e32 v38, v0
	v_mov_b32_e32 v39, v0
	v_mov_b32_e32 v44, v0
	v_mov_b32_e32 v45, v0
	v_mov_b32_e32 v46, v0
	v_mov_b32_e32 v47, v0
	v_mov_b32_e32 v52, v0
	v_mov_b32_e32 v53, v0
	v_mov_b32_e32 v54, v0
	v_mov_b32_e32 v55, v0
	v_mov_b32_e32 v60, v0
	v_mov_b32_e32 v61, v0
	v_mov_b32_e32 v62, v0
	v_mov_b32_e32 v63, v0
	v_mov_b32_e32 v64, v0
	v_mov_b32_e32 v65, v0
	v_mov_b32_e32 v66, v0
	v_mov_b32_e32 v67, v0
	v_mov_b32_e32 v72, v0
	v_mov_b32_e32 v73, v0
	v_mov_b32_e32 v74, v0
	v_mov_b32_e32 v75, v0
	v_mov_b32_e32 v80, v0
	v_mov_b32_e32 v81, v0
	v_mov_b32_e32 v82, v0
	v_mov_b32_e32 v83, v0
	v_mov_b32_e32 v88, v0
	v_mov_b32_e32 v89, v0
	v_mov_b32_e32 v90, v0
	v_mov_b32_e32 v91, v0
	v_mov_b32_e32 v96, v0
	v_mov_b32_e32 v97, v0
	v_mov_b32_e32 v98, v0
	v_mov_b32_e32 v99, v0
	v_mov_b32_e32 v104, v0
	v_mov_b32_e32 v105, v0
	v_mov_b32_e32 v106, v0
	v_mov_b32_e32 v107, v0
	v_mov_b32_e32 v112, v0
	v_mov_b32_e32 v113, v0
	v_mov_b32_e32 v114, v0
	v_mov_b32_e32 v115, v0
	v_mov_b32_e32 v120, v0
	v_mov_b32_e32 v121, v0
	v_mov_b32_e32 v122, v0
	v_mov_b32_e32 v123, v0
	v_mov_b32_e32 v68, v0
	v_mov_b32_e32 v69, v0
	v_mov_b32_e32 v70, v0
	v_mov_b32_e32 v71, v0
	v_mov_b32_e32 v76, v0
	v_mov_b32_e32 v77, v0
	v_mov_b32_e32 v78, v0
	v_mov_b32_e32 v79, v0
	v_mov_b32_e32 v84, v0
	v_mov_b32_e32 v85, v0
	v_mov_b32_e32 v86, v0
	v_mov_b32_e32 v87, v0
	v_mov_b32_e32 v92, v0
	v_mov_b32_e32 v93, v0
	v_mov_b32_e32 v94, v0
	v_mov_b32_e32 v95, v0
	v_mov_b32_e32 v100, v0
	v_mov_b32_e32 v101, v0
	v_mov_b32_e32 v102, v0
	v_mov_b32_e32 v103, v0
	v_mov_b32_e32 v108, v0
	v_mov_b32_e32 v109, v0
	v_mov_b32_e32 v110, v0
	v_mov_b32_e32 v111, v0
	v_mov_b32_e32 v116, v0
	v_mov_b32_e32 v117, v0
	v_mov_b32_e32 v118, v0
	v_mov_b32_e32 v119, v0
	v_mov_b32_e32 v124, v0
	v_mov_b32_e32 v125, v0
	v_mov_b32_e32 v126, v0
	v_mov_b32_e32 v127, v0
	.p2align	6

; template <class Epi>
; __device__ __forceinline__ void gemm_phase(LAS unsigned char* lds, const Gemm g, const StaticOrder& S, const Epi& E) {
;     ...
;         const bool has_next = S.next(ui + 1, nxt);
;         const char* nA = has_next ? (const char*)g.A + (size_t)nxt.pm * tstep : cA; const char* nB = has_next ? (const char*)g.Bt + (size_t)nxt.pn * tstep : cB;
;         for (int t = 0; t < nt; t += 2) {
;             const bool last = (t == nt - 2);
;             const char* a1 = cA + (size_t)(t + 1) * kstep;
;             const char* a2 = last ? nA : cA + (size_t)(t + 2) * kstep; const char* b2 = last ? nB : cB + (size_t)(t + 2) * kstep;
;             const char* a3 = a2 + kstep; const char* b3 = b2 + kstep;
;     ...
; #pragma unroll
;         for (int a = 0; a < 2; ++a)
; #pragma unroll
;             for (int b = 0; b < 2; ++b)
; #pragma unroll
;                 for (int m = 0; m < 4; ++m)
; #pragma unroll
;                     for (int n = 0; n < 2; ++n) acc[a][b][m][n] = (f32x4){0.f, 0.f, 0.f, 0.f};
;         cur = nxt; cA = nA; cB = nB; ++ui;
.LBB0_2625:
	s_add_u32 s18, s18, 0x158080
	s_addc_u32 s19, s19, 0
	s_add_u32 s62, s20, 0x100
	v_mov_b32_e32 v0, 0
	s_addc_u32 s63, s21, 0
	s_mov_b32 s64, -2
	v_mov_b32_e32 v1, v0
	v_mov_b32_e32 v2, v0
	v_mov_b32_e32 v3, v0
	v_mov_b32_e32 v4, v0
	v_mov_b32_e32 v5, v0
	v_mov_b32_e32 v6, v0
	v_mov_b32_e32 v7, v0
	v_mov_b32_e32 v8, v0
	v_mov_b32_e32 v9, v0
	v_mov_b32_e32 v10, v0
	v_mov_b32_e32 v11, v0
	v_mov_b32_e32 v16, v0
	v_mov_b32_e32 v17, v0
	v_mov_b32_e32 v18, v0
	v_mov_b32_e32 v19, v0
	v_mov_b32_e32 v32, v0
	v_mov_b32_e32 v33, v0
	v_mov_b32_e32 v34, v0
	v_mov_b32_e32 v35, v0
	v_mov_b32_e32 v36, v0
	v_mov_b32_e32 v37, v0
	v_mov_b32_e32 v38, v0
	v_mov_b32_e32 v39, v0
	v_mov_b32_e32 v44, v0
	v_mov_b32_e32 v45, v0
	v_mov_b32_e32 v46, v0
	v_mov_b32_e32 v47, v0
	v_mov_b32_e32 v52, v0
	v_mov_b32_e32 v53, v0
	v_mov_b32_e32 v54, v0
	v_mov_b32_e32 v55, v0
	v_mov_b32_e32 v12, v0
	v_mov_b32_e32 v13, v0
	v_mov_b32_e32 v14, v0
	v_mov_b32_e32 v15, v0
	v_mov_b32_e32 v20, v0
	v_mov_b32_e32 v21, v0
	v_mov_b32_e32 v22, v0
	v_mov_b32_e32 v23, v0
	v_mov_b32_e32 v24, v0
	v_mov_b32_e32 v25, v0
	v_mov_b32_e32 v26, v0
	v_mov_b32_e32 v27, v0
	v_mov_b32_e32 v28, v0
	v_mov_b32_e32 v29, v0
	v_mov_b32_e32 v30, v0
	v_mov_b32_e32 v31, v0
	v_mov_b32_e32 v40, v0
	v_mov_b32_e32 v41, v0
	v_mov_b32_e32 v42, v0
	v_mov_b32_e32 v43, v0
	v_mov_b32_e32 v48, v0
	v_mov_b32_e32 v49, v0
	v_mov_b32_e32 v50, v0
	v_mov_b32_e32 v51, v0
	v_mov_b32_e32 v56, v0
	v_mov_b32_e32 v57, v0
	v_mov_b32_e32 v58, v0
	v_mov_b32_e32 v59, v0
	v_mov_b32_e32 v60, v0
	v_mov_b32_e32 v61, v0
	v_mov_b32_e32 v62, v0
	v_mov_b32_e32 v63, v0
	v_mov_b32_e32 v64, v0
	v_mov_b32_e32 v65, v0
	v_mov_b32_e32 v66, v0
	v_mov_b32_e32 v67, v0
	v_mov_b32_e32 v68, v0
	v_mov_b32_e32 v69, v0
	v_mov_b32_e32 v70, v0
	v_mov_b32_e32 v71, v0
	v_mov_b32_e32 v76, v0
	v_mov_b32_e32 v77, v0
	v_mov_b32_e32 v78, v0
	v_mov_b32_e32 v79, v0
	v_mov_b32_e32 v84, v0
	v_mov_b32_e32 v85, v0
	v_mov_b32_e32 v86, v0
	v_mov_b32_e32 v87, v0
	v_mov_b32_e32 v96, v0
	v_mov_b32_e32 v97, v0
	v_mov_b32_e32 v98, v0
	v_mov_b32_e32 v99, v0
	v_mov_b32_e32 v100, v0
	v_mov_b32_e32 v101, v0
	v_mov_b32_e32 v102, v0
	v_mov_b32_e32 v103, v0
	v_mov_b32_e32 v108, v0
	v_mov_b32_e32 v109, v0
	v_mov_b32_e32 v110, v0
	v_mov_b32_e32 v111, v0
	v_mov_b32_e32 v116, v0
	v_mov_b32_e32 v117, v0
	v_mov_b32_e32 v118, v0
	v_mov_b32_e32 v119, v0
	v_mov_b32_e32 v72, v0
	v_mov_b32_e32 v73, v0
	v_mov_b32_e32 v74, v0
	v_mov_b32_e32 v75, v0
	v_mov_b32_e32 v80, v0
	v_mov_b32_e32 v81, v0
	v_mov_b32_e32 v82, v0
	v_mov_b32_e32 v83, v0
	v_mov_b32_e32 v88, v0
	v_mov_b32_e32 v89, v0
	v_mov_b32_e32 v90, v0
	v_mov_b32_e32 v91, v0
	v_mov_b32_e32 v92, v0
	v_mov_b32_e32 v93, v0
	v_mov_b32_e32 v94, v0
	v_mov_b32_e32 v95, v0
	v_mov_b32_e32 v104, v0
	v_mov_b32_e32 v105, v0
	v_mov_b32_e32 v106, v0
	v_mov_b32_e32 v107, v0
	v_mov_b32_e32 v112, v0
	v_mov_b32_e32 v113, v0
	v_mov_b32_e32 v114, v0
	v_mov_b32_e32 v115, v0
	v_mov_b32_e32 v120, v0
	v_mov_b32_e32 v121, v0
	v_mov_b32_e32 v122, v0
	v_mov_b32_e32 v123, v0
	v_mov_b32_e32 v124, v0
	v_mov_b32_e32 v125, v0
	v_mov_b32_e32 v126, v0
	v_mov_b32_e32 v127, v0
	.p2align	6
